# E38: layer-0 mixer queue order: pool units first, memory-attention units last (smaller tail granularity); on E35
# baseline (speedup 1.0000x reference)
.LBB0_320:
	s_or_b64 exec, exec, s[4:5]
	s_waitcnt lgkmcnt(0)
	s_barrier
	ds_read_b32 v4, v3
	s_movk_i32 s4, 0x5bf
	s_waitcnt lgkmcnt(0)
	v_cmp_lt_i32_e32 vcc, s4, v4
	v_readfirstlane_b32 s18, v4
	s_mov_b64 s[4:5], -1
	s_cbranch_vccnz .LBB0_315
	s_cmpk_lt_i32 s18, 0x500
	s_cselect_b64 s[4:5], -1, 0
	s_cmpk_gt_i32 s18, 0x4ff
	s_cselect_b64 s[6:7], -1, 0
	s_bitcmp1_b32 s18, 0
	s_cselect_b64 s[40:41], -1, 0
	s_or_b64 s[40:41], s[6:7], s[40:41]
	s_ashr_i32 s91, s18, 1
	s_mov_b64 s[6:7], -1
	s_and_b64 vcc, exec, s[40:41]
	s_cbranch_vccz .LBB0_439
	s_addk_i32 s18, 0xfd80
	s_and_b64 s[4:5], s[4:5], exec
	s_cselect_b32 s96, s91, s18
	s_add_i32 s4, s96, 0x100
	s_add_i32 s5, s96, 0xfffffde0
	s_cmpk_lt_u32 s96, 0x220
	s_cselect_b32 s4, s4, s5
	s_cmpk_lt_u32 s96, 0x320
	s_cselect_b32 s96, s4, s96
	s_add_i32 s69, s96, 0xffffff00
	s_cmpk_gt_u32 s69, 0x21f
	s_mov_b64 s[4:5], -1
	s_cbranch_scc0 .LBB0_420
	s_add_i32 s4, s96, 0xfffffde0
	s_cmpk_lt_i32 s96, 0x100
	s_cselect_b32 s48, s96, s4
	s_cmpk_gt_i32 s48, 0xff
	s_cselect_b64 s[4:5], -1, 0
	s_mov_b64 s[46:47], -1
	s_and_b64 vcc, exec, s[4:5]
	s_cbranch_vccz .LBB0_325
	s_add_i32 s6, s48, 0xffffff00
	s_lshr_b32 s6, s6, 2
	s_lshl_b32 s7, s6, 4
	s_add_i32 s18, s7, 0x4000
	s_mov_b32 s7, s19
	s_lshl_b64 s[6:7], s[6:7], 18
	s_add_u32 s42, s67, s6
	s_addc_u32 s43, s70, s7
	s_lshl_b32 s40, s48, 7
	s_and_b32 s40, s40, 0x180
	s_lshl_b32 s44, s40, 1
	s_add_u32 s42, s42, s44
	s_addc_u32 s43, s43, 0
	s_add_u32 s6, s77, s6
	s_addc_u32 s7, s78, s7
	s_add_u32 s44, s6, s44
	s_mov_b32 s41, s19
	s_addc_u32 s45, s7, 0
	s_mov_b64 s[46:47], 0
	s_mov_b64 s[6:7], s[18:19]
	s_mov_b32 s18, s40
